# adds hand-written EpiAct epilogue (separate fused-norm and plain paths) for the first W1 GEMM to mod_item rewrite + item rotation + bare v_sqrt + P2b epilogue
# speedup vs baseline: 1.0116x; 1.0011x over previous
; template <class Epi>
; DEVI void gemm_phase(const Params& p, const u16* __restrict__ A, const u16* __restrict__ Bt, const int M, const int N, const int K, const int Msplit, const Epi& epi) {
;     ...
;       if constexpr (Epi::NRM) {
;         nrm = epi.ssq != nullptr && brow < TL;
;         if (nrm) {
;           if (tid2 < 256) { const float* q = epi.ssq + brow + tid2; rl[tid2] = rsqrtf(((q[0] + q[T]) + (q[2 * T] + q[3 * T])) * (1.f / D) + 1e-6f); }
;           WAIT_L(0); BAR;
;         }
;       }
; #pragma unroll
;       for (int ai = 0; ai < 2; ++ai)
; #pragma unroll
;         for (int bj = 0; bj < 2; ++bj) {
;           const int colb = bcol + bj * HALF + wc2 * 32;
;           typename Epi::Pre pre;
;           if constexpr (Epi::NRM || Epi::SQ) epi.preload(pre, brow, colb, wr2, fr2, fq2, nrm, slcur);
; #pragma unroll
;           for (int m = 0; m < 4; ++m) {
;             const int rloc = ai * HALF + wr2 * 64 + m * 16;
;             if constexpr (Epi::SQ) epi(brow + rloc + fr2, colb, fq2, acc[ai][bj][m][0], acc[ai][bj][m][1], sq[ai * 4 + m], slcur, pre);
;             else if constexpr (Epi::TR) { float rv = 1.f; if (nrm) rv = rl[rloc + fr2]; epi(brow + rloc + fr2, colb, fq2, acc[ai][bj][m][0], acc[ai][bj][m][1], rv, nrm, pre); }
;             else { f32x4 rv = {1.f, 1.f, 1.f, 1.f}; if (nrm) rv = *(const f32x4*)(rl + rloc + fq2 * 4); epi(brow + rloc + fq2 * 4, colb, fr2, acc[ai][bj][m][0], acc[ai][bj][m][1], rv, nrm, pre); }
;           }
;         }
;   DEVI void preload(Pre& q, int brow, int colb, int wr, int fr, int fq, bool nrm, int) const {
;     if (nrm) { const int r = brow < TL ? (brow >> 12) : 8; q.sa = *(const f32x4*)(sw + (size_t)r * 5632 + colb + 4 * fq); q.sb = *(const f32x4*)(sw + (size_t)r * 5632 + colb + 16 + 4 * fq); }
;   }
;   DEVI void operator()(int row, int colb, int fq, const f32x4& a0, const f32x4& a1, const float rinv, const bool nrm, const Pre& q) const {
;     const int oc = (colb >> 5) * 16 + 4 * fq;
;     f32x4 xa = a0, xb = a1;
;     if (nrm) {
; #pragma unroll
;       for (int j = 0; j < 4; ++j) { xa[j] = xa[j] * rinv + q.sa[j]; xb[j] = xb[j] * rinv + q.sb[j]; }
;     }
;     float v[4];
; #pragma unroll
;     for (int j = 0; j < 4; ++j) { const float a = xa[j]; v[j] = a * sigmoidf_(a) * xb[j]; }
;     uint2 o; o.x = pk_bf16(v[0], v[1]); o.y = pk_bf16(v[2], v[3]);
;     *(uint2*)(act + (size_t)row * DFF + oc) = o;
.LBB0_698:
	s_branch .Lmy_p2_epi
	v_lshrrev_b32_e32 v136, 1, v140
	v_lshrrev_b32_e32 v137, 2, v142
	v_and_b32_e32 v136, 0x60, v136
	v_and_b32_e32 v145, 12, v137
	s_lshr_b32 s16, s16, 4
	v_or_b32_e32 v136, s18, v136
	s_mulk_i32 s16, 0x5800
	s_and_b64 vcc, exec, s[10:11]
	v_lshlrev_b32_e32 v138, 2, v145
	s_cbranch_vccnz .LBB0_700
	v_readlane_b32 s17, v253, 49
	s_add_u32 s18, s17, s16
	v_readlane_b32 s17, v253, 50
	s_addc_u32 s19, s17, 0
	v_mov_b32_e32 v137, v213
	s_waitcnt vmcnt(0)
	v_lshl_add_u64 v[0:1], v[136:137], 2, s[18:19]
	v_mov_b32_e32 v139, v213
	v_lshl_add_u64 v[4:5], v[0:1], 0, v[138:139]
	global_load_dwordx4 v[0:3], v[4:5], off
	s_nop 0
	global_load_dwordx4 v[4:7], v[4:5], off offset:64

; template <class Epi>
; DEVI void gemm_phase(const Params& p, const u16* __restrict__ A, const u16* __restrict__ Bt, const int M, const int N, const int K, const int Msplit, const Epi& epi) {
;     ...
;             else if constexpr (Epi::TR) { float rv = 1.f; if (nrm) rv = rl[rloc + fr2]; epi(brow + rloc + fr2, colb, fq2, acc[ai][bj][m][0], acc[ai][bj][m][1], rv, nrm, pre); }
;   DEVI void preload(Pre& q, int brow, int colb, int wr, int fr, int fq, bool nrm, int) const {
;     if (nrm) { const int r = brow < TL ? (brow >> 12) : 8; q.sa = *(const f32x4*)(sw + (size_t)r * 5632 + colb + 4 * fq); q.sb = *(const f32x4*)(sw + (size_t)r * 5632 + colb + 16 + 4 * fq); }
;   }
;   DEVI void operator()(int row, int colb, int fq, const f32x4& a0, const f32x4& a1, const float rinv, const bool nrm, const Pre& q) const {
;     const int oc = (colb >> 5) * 16 + 4 * fq;
;     f32x4 xa = a0, xb = a1;
;     if (nrm) {
; #pragma unroll
;       for (int j = 0; j < 4; ++j) { xa[j] = xa[j] * rinv + q.sa[j]; xb[j] = xb[j] * rinv + q.sb[j]; }
;     }
.Lmy_p2_epi:
	v_mbcnt_lo_u32_b32 v200, -1, 0
	v_mbcnt_hi_u32_b32 v200, -1, v200
	s_lshr_b32 s52, s33, 6
	s_lshr_b32 s53, s52, 2
	s_and_b32 s52, s52, 3
	s_lshl_b32 s55, s53, 8
	s_mul_i32 s53, s53, 0x58000
	s_lshl_b32 s52, s52, 5
	v_and_b32_e32 v201, 15, v200
	v_lshrrev_b32_e32 v200, 4, v200
	v_lshl_add_u32 v203, v201, 2, s55
	v_lshlrev_b32_e32 v202, 4, v200
	v_mul_u32_u24_e32 v201, 0x1600, v201
	s_lshl_b32 s55, s52, 2
	v_add_u32_e32 v202, s55, v202
	s_add_u32 s52, s52, s53
	v_lshl_add_u32 v200, v200, 3, s52
	v_add_u32_e32 v192, v200, v201
	v_add_u32_e32 v193, 0x16000, v192
	v_add_u32_e32 v194, 0x2c000, v192
	v_add_u32_e32 v195, 0x42000, v192
	v_mov_b32_e32 v196, 1.0
	v_mov_b32_e32 v197, 1.0
	v_mov_b32_e32 v198, 0xbfb8aa3b
	v_mov_b32_e32 v199, 0xbfb8aa3b
	s_mul_i32 s54, s90, 0x1600
	s_add_u32 s54, s54, s18
	s_add_u32 s44, s60, s54
	s_addc_u32 s45, s61, 0
	s_add_u32 s46, s44, 0xb0000
	s_addc_u32 s47, s45, 0
	s_and_b64 vcc, exec, s[12:13]
	s_cbranch_vccz .Lmy_p2_plain
	v_readlane_b32 s56, v253, 49
	v_readlane_b32 s57, v253, 50
	s_lshr_b32 s54, s16, 4
	s_mul_i32 s54, s54, 0x5800
	s_lshl_b32 s55, s18, 2
	s_add_u32 s54, s54, s55
	s_add_u32 s56, s56, s54
	s_addc_u32 s57, s57, 0
	global_load_dwordx4 v[152:155], v202, s[56:57]
	global_load_dwordx4 v[156:159], v202, s[56:57] offset:64
	global_load_dwordx4 v[160:163], v202, s[56:57] offset:512
	global_load_dwordx4 v[164:167], v202, s[56:57] offset:576
	ds_read_b32 v168, v203 offset:49152
	ds_read_b32 v169, v203 offset:49216
	ds_read_b32 v170, v203 offset:49280
	ds_read_b32 v171, v203 offset:49344
	ds_read_b32 v172, v203 offset:49664
	ds_read_b32 v173, v203 offset:49728
	ds_read_b32 v174, v203 offset:49792
	ds_read_b32 v175, v203 offset:49856
	s_waitcnt vmcnt(0) lgkmcnt(0)
	v_fma_f32 v128, v128, v168, v152
	v_fma_f32 v129, v129, v168, v153
	v_fma_f32 v130, v130, v168, v154
	v_fma_f32 v131, v131, v168, v155
	v_fma_f32 v132, v132, v168, v156
	v_fma_f32 v133, v133, v168, v157
	v_fma_f32 v134, v134, v168, v158
	v_fma_f32 v135, v135, v168, v159
	v_fma_f32 v120, v120, v169, v152
	v_fma_f32 v121, v121, v169, v153
	v_fma_f32 v122, v122, v169, v154
	v_fma_f32 v123, v123, v169, v155
	v_fma_f32 v124, v124, v169, v156
	v_fma_f32 v125, v125, v169, v157
	v_fma_f32 v126, v126, v169, v158
	v_fma_f32 v127, v127, v169, v159
	v_fma_f32 v112, v112, v170, v152
	v_fma_f32 v113, v113, v170, v153
	v_fma_f32 v114, v114, v170, v154
	v_fma_f32 v115, v115, v170, v155
	v_fma_f32 v116, v116, v170, v156
	v_fma_f32 v117, v117, v170, v157
	v_fma_f32 v118, v118, v170, v158
	v_fma_f32 v119, v119, v170, v159
	v_fma_f32 v104, v104, v171, v152
	v_fma_f32 v105, v105, v171, v153
	v_fma_f32 v106, v106, v171, v154
	v_fma_f32 v107, v107, v171, v155
	v_fma_f32 v108, v108, v171, v156
	v_fma_f32 v109, v109, v171, v157
	v_fma_f32 v110, v110, v171, v158
	v_fma_f32 v111, v111, v171, v159
	v_fma_f32 v96, v96, v168, v160
	v_fma_f32 v97, v97, v168, v161
	v_fma_f32 v98, v98, v168, v162
	v_fma_f32 v99, v99, v168, v163
	v_fma_f32 v100, v100, v168, v164
	v_fma_f32 v101, v101, v168, v165
	v_fma_f32 v102, v102, v168, v166
	v_fma_f32 v103, v103, v168, v167
	v_fma_f32 v88, v88, v169, v160
	v_fma_f32 v89, v89, v169, v161
	v_fma_f32 v90, v90, v169, v162
	v_fma_f32 v91, v91, v169, v163
	v_fma_f32 v92, v92, v169, v164
	v_fma_f32 v93, v93, v169, v165
	v_fma_f32 v94, v94, v169, v166
	v_fma_f32 v95, v95, v169, v167
	v_fma_f32 v80, v80, v170, v160
	v_fma_f32 v81, v81, v170, v161
	v_fma_f32 v82, v82, v170, v162
	v_fma_f32 v83, v83, v170, v163
	v_fma_f32 v84, v84, v170, v164
	v_fma_f32 v85, v85, v170, v165
	v_fma_f32 v86, v86, v170, v166
	v_fma_f32 v87, v87, v170, v167
	v_fma_f32 v72, v72, v171, v160
	v_fma_f32 v73, v73, v171, v161
	v_fma_f32 v74, v74, v171, v162
	v_fma_f32 v75, v75, v171, v163
	v_fma_f32 v76, v76, v171, v164
	v_fma_f32 v77, v77, v171, v165
	v_fma_f32 v78, v78, v171, v166
	v_fma_f32 v79, v79, v171, v167
	v_fma_f32 v64, v64, v172, v152
	v_fma_f32 v65, v65, v172, v153
	v_fma_f32 v66, v66, v172, v154
	v_fma_f32 v67, v67, v172, v155
	v_fma_f32 v68, v68, v172, v156
	v_fma_f32 v69, v69, v172, v157
	v_fma_f32 v70, v70, v172, v158
	v_fma_f32 v71, v71, v172, v159
	v_fma_f32 v56, v56, v173, v152
	v_fma_f32 v57, v57, v173, v153
	v_fma_f32 v58, v58, v173, v154
	v_fma_f32 v59, v59, v173, v155
	v_fma_f32 v60, v60, v173, v156
	v_fma_f32 v61, v61, v173, v157
	v_fma_f32 v62, v62, v173, v158
	v_fma_f32 v63, v63, v173, v159
	v_fma_f32 v48, v48, v174, v152
	v_fma_f32 v49, v49, v174, v153
	v_fma_f32 v50, v50, v174, v154
	v_fma_f32 v51, v51, v174, v155
	v_fma_f32 v52, v52, v174, v156
	v_fma_f32 v53, v53, v174, v157
	v_fma_f32 v54, v54, v174, v158
	v_fma_f32 v55, v55, v174, v159
	v_fma_f32 v40, v40, v175, v152
	v_fma_f32 v41, v41, v175, v153
	v_fma_f32 v42, v42, v175, v154
	v_fma_f32 v43, v43, v175, v155
	v_fma_f32 v44, v44, v175, v156
	v_fma_f32 v45, v45, v175, v157
	v_fma_f32 v46, v46, v175, v158
	v_fma_f32 v47, v47, v175, v159
	v_fma_f32 v32, v32, v172, v160
	v_fma_f32 v33, v33, v172, v161
	v_fma_f32 v34, v34, v172, v162
	v_fma_f32 v35, v35, v172, v163
	v_fma_f32 v36, v36, v172, v164
	v_fma_f32 v37, v37, v172, v165
	v_fma_f32 v38, v38, v172, v166
	v_fma_f32 v39, v39, v172, v167
	v_fma_f32 v24, v24, v173, v160
	v_fma_f32 v25, v25, v173, v161
	v_fma_f32 v26, v26, v173, v162
	v_fma_f32 v27, v27, v173, v163
	v_fma_f32 v28, v28, v173, v164
	v_fma_f32 v29, v29, v173, v165
	v_fma_f32 v30, v30, v173, v166
	v_fma_f32 v31, v31, v173, v167
	v_fma_f32 v16, v16, v174, v160
	v_fma_f32 v17, v17, v174, v161
	v_fma_f32 v18, v18, v174, v162
	v_fma_f32 v19, v19, v174, v163
	v_fma_f32 v20, v20, v174, v164
	v_fma_f32 v21, v21, v174, v165
	v_fma_f32 v22, v22, v174, v166
	v_fma_f32 v23, v23, v174, v167
	v_fma_f32 v8, v8, v175, v160
	v_fma_f32 v9, v9, v175, v161
	v_fma_f32 v10, v10, v175, v162
	v_fma_f32 v11, v11, v175, v163
	v_fma_f32 v12, v12, v175, v164
	v_fma_f32 v13, v13, v175, v165
	v_fma_f32 v14, v14, v175, v166
	v_fma_f32 v15, v15, v175, v167
; DEVI unsigned pk_bf16(float lo, float hi) { unsigned r; asm volatile("v_cvt_pk_bf16_f32 %0, %1, %2" : "=v"(r) : "v"(lo), "v"(hi)); return r; }
; DEVI float sigmoidf_(float x) { return __builtin_amdgcn_rcpf(1.f + __expf(-x)); }
;   DEVI void operator()(int row, int colb, int fq, const f32x4& a0, const f32x4& a1, const float rinv, const bool nrm, const Pre& q) const {
;     ...
;     float v[4];
; #pragma unroll
;     for (int j = 0; j < 4; ++j) { const float a = xa[j]; v[j] = a * sigmoidf_(a) * xb[j]; }
;     uint2 o; o.x = pk_bf16(v[0], v[1]); o.y = pk_bf16(v[2], v[3]);
;     *(uint2*)(act + (size_t)row * DFF + oc) = o;
.Lmy_p2_plain:
	v_pk_mul_f32 v[176:177], v[128:129], v[198:199]
	v_pk_mul_f32 v[178:179], v[130:131], v[198:199]
	v_pk_mul_f32 v[184:185], v[120:121], v[198:199]
	v_pk_mul_f32 v[186:187], v[122:123], v[198:199]
	v_exp_f32_e32 v176, v176
	v_exp_f32_e32 v177, v177
	v_exp_f32_e32 v178, v178
	v_exp_f32_e32 v179, v179
	v_exp_f32_e32 v184, v184
	v_exp_f32_e32 v185, v185
	v_exp_f32_e32 v186, v186
	v_exp_f32_e32 v187, v187
	v_pk_add_f32 v[176:177], v[196:197], v[176:177]
	v_pk_add_f32 v[178:179], v[196:197], v[178:179]
	v_pk_add_f32 v[184:185], v[196:197], v[184:185]
	v_pk_add_f32 v[186:187], v[196:197], v[186:187]
	v_rcp_f32_e32 v176, v176
	v_rcp_f32_e32 v177, v177
	v_rcp_f32_e32 v178, v178
	v_rcp_f32_e32 v179, v179
	v_rcp_f32_e32 v184, v184
	v_rcp_f32_e32 v185, v185
	v_rcp_f32_e32 v186, v186
	v_rcp_f32_e32 v187, v187
	v_pk_mul_f32 v[128:129], v[128:129], v[176:177]
	v_pk_mul_f32 v[130:131], v[130:131], v[178:179]
	v_pk_mul_f32 v[120:121], v[120:121], v[184:185]
	v_pk_mul_f32 v[122:123], v[122:123], v[186:187]
	v_pk_mul_f32 v[128:129], v[132:133], v[128:129]
	v_pk_mul_f32 v[130:131], v[134:135], v[130:131]
	v_pk_mul_f32 v[120:121], v[124:125], v[120:121]
	v_pk_mul_f32 v[122:123], v[126:127], v[122:123]
	v_cvt_pk_bf16_f32 v132, v128, v129
	v_cvt_pk_bf16_f32 v133, v130, v131
	v_cvt_pk_bf16_f32 v124, v120, v121
	v_cvt_pk_bf16_f32 v125, v122, v123
	global_store_dwordx2 v192, v[132:133], s[44:45]
	global_store_dwordx2 v193, v[124:125], s[44:45]
	v_pk_mul_f32 v[176:177], v[112:113], v[198:199]
	v_pk_mul_f32 v[178:179], v[114:115], v[198:199]
	v_pk_mul_f32 v[184:185], v[104:105], v[198:199]
	v_pk_mul_f32 v[186:187], v[106:107], v[198:199]
	v_exp_f32_e32 v176, v176
	v_exp_f32_e32 v177, v177
	v_exp_f32_e32 v178, v178
	v_exp_f32_e32 v179, v179
	v_exp_f32_e32 v184, v184
	v_exp_f32_e32 v185, v185
	v_exp_f32_e32 v186, v186
	v_exp_f32_e32 v187, v187
	v_pk_add_f32 v[176:177], v[196:197], v[176:177]
	v_pk_add_f32 v[178:179], v[196:197], v[178:179]
	v_pk_add_f32 v[184:185], v[196:197], v[184:185]
	v_pk_add_f32 v[186:187], v[196:197], v[186:187]
	v_rcp_f32_e32 v176, v176
	v_rcp_f32_e32 v177, v177
	v_rcp_f32_e32 v178, v178
	v_rcp_f32_e32 v179, v179
	v_rcp_f32_e32 v184, v184
	v_rcp_f32_e32 v185, v185
	v_rcp_f32_e32 v186, v186
	v_rcp_f32_e32 v187, v187
	v_pk_mul_f32 v[112:113], v[112:113], v[176:177]
	v_pk_mul_f32 v[114:115], v[114:115], v[178:179]
	v_pk_mul_f32 v[104:105], v[104:105], v[184:185]
	v_pk_mul_f32 v[106:107], v[106:107], v[186:187]
	v_pk_mul_f32 v[112:113], v[116:117], v[112:113]
	v_pk_mul_f32 v[114:115], v[118:119], v[114:115]
	v_pk_mul_f32 v[104:105], v[108:109], v[104:105]
	v_pk_mul_f32 v[106:107], v[110:111], v[106:107]
	v_cvt_pk_bf16_f32 v116, v112, v113
	v_cvt_pk_bf16_f32 v117, v114, v115
	v_cvt_pk_bf16_f32 v108, v104, v105
	v_cvt_pk_bf16_f32 v109, v106, v107
	global_store_dwordx2 v194, v[116:117], s[44:45]
	global_store_dwordx2 v195, v[108:109], s[44:45]
	v_pk_mul_f32 v[176:177], v[96:97], v[198:199]
	v_pk_mul_f32 v[178:179], v[98:99], v[198:199]
	v_pk_mul_f32 v[184:185], v[88:89], v[198:199]
	v_pk_mul_f32 v[186:187], v[90:91], v[198:199]
	v_exp_f32_e32 v176, v176
	v_exp_f32_e32 v177, v177
	v_exp_f32_e32 v178, v178
	v_exp_f32_e32 v179, v179
	v_exp_f32_e32 v184, v184
	v_exp_f32_e32 v185, v185
	v_exp_f32_e32 v186, v186
	v_exp_f32_e32 v187, v187
	v_pk_add_f32 v[176:177], v[196:197], v[176:177]
	v_pk_add_f32 v[178:179], v[196:197], v[178:179]
	v_pk_add_f32 v[184:185], v[196:197], v[184:185]
	v_pk_add_f32 v[186:187], v[196:197], v[186:187]
	v_rcp_f32_e32 v176, v176
	v_rcp_f32_e32 v177, v177
	v_rcp_f32_e32 v178, v178
	v_rcp_f32_e32 v179, v179
	v_rcp_f32_e32 v184, v184
	v_rcp_f32_e32 v185, v185
	v_rcp_f32_e32 v186, v186
	v_rcp_f32_e32 v187, v187
	v_pk_mul_f32 v[96:97], v[96:97], v[176:177]
	v_pk_mul_f32 v[98:99], v[98:99], v[178:179]
	v_pk_mul_f32 v[88:89], v[88:89], v[184:185]
	v_pk_mul_f32 v[90:91], v[90:91], v[186:187]
	v_pk_mul_f32 v[96:97], v[100:101], v[96:97]
	v_pk_mul_f32 v[98:99], v[102:103], v[98:99]
	v_pk_mul_f32 v[88:89], v[92:93], v[88:89]
	v_pk_mul_f32 v[90:91], v[94:95], v[90:91]
	v_cvt_pk_bf16_f32 v100, v96, v97
	v_cvt_pk_bf16_f32 v101, v98, v99
	v_cvt_pk_bf16_f32 v92, v88, v89
	v_cvt_pk_bf16_f32 v93, v90, v91
	global_store_dwordx2 v192, v[100:101], s[44:45] offset:128
	global_store_dwordx2 v193, v[92:93], s[44:45] offset:128
	v_pk_mul_f32 v[176:177], v[80:81], v[198:199]
	v_pk_mul_f32 v[178:179], v[82:83], v[198:199]
	v_pk_mul_f32 v[184:185], v[72:73], v[198:199]
	v_pk_mul_f32 v[186:187], v[74:75], v[198:199]
	v_exp_f32_e32 v176, v176
	v_exp_f32_e32 v177, v177
	v_exp_f32_e32 v178, v178
	v_exp_f32_e32 v179, v179
	v_exp_f32_e32 v184, v184
	v_exp_f32_e32 v185, v185
	v_exp_f32_e32 v186, v186
	v_exp_f32_e32 v187, v187
	v_pk_add_f32 v[176:177], v[196:197], v[176:177]
	v_pk_add_f32 v[178:179], v[196:197], v[178:179]
	v_pk_add_f32 v[184:185], v[196:197], v[184:185]
	v_pk_add_f32 v[186:187], v[196:197], v[186:187]
	v_rcp_f32_e32 v176, v176
	v_rcp_f32_e32 v177, v177
	v_rcp_f32_e32 v178, v178
	v_rcp_f32_e32 v179, v179
	v_rcp_f32_e32 v184, v184
	v_rcp_f32_e32 v185, v185
	v_rcp_f32_e32 v186, v186
	v_rcp_f32_e32 v187, v187
	v_pk_mul_f32 v[80:81], v[80:81], v[176:177]
	v_pk_mul_f32 v[82:83], v[82:83], v[178:179]
	v_pk_mul_f32 v[72:73], v[72:73], v[184:185]
	v_pk_mul_f32 v[74:75], v[74:75], v[186:187]
	v_pk_mul_f32 v[80:81], v[84:85], v[80:81]
	v_pk_mul_f32 v[82:83], v[86:87], v[82:83]
	v_pk_mul_f32 v[72:73], v[76:77], v[72:73]
	v_pk_mul_f32 v[74:75], v[78:79], v[74:75]
	v_cvt_pk_bf16_f32 v84, v80, v81
	v_cvt_pk_bf16_f32 v85, v82, v83
	v_cvt_pk_bf16_f32 v76, v72, v73
	v_cvt_pk_bf16_f32 v77, v74, v75
	global_store_dwordx2 v194, v[84:85], s[44:45] offset:128
; DEVI unsigned pk_bf16(float lo, float hi) { unsigned r; asm volatile("v_cvt_pk_bf16_f32 %0, %1, %2" : "=v"(r) : "v"(lo), "v"(hi)); return r; }
; DEVI float sigmoidf_(float x) { return __builtin_amdgcn_rcpf(1.f + __expf(-x)); }
;   DEVI void operator()(int row, int colb, int fq, const f32x4& a0, const f32x4& a1, const float rinv, const bool nrm, const Pre& q) const {
;     ...
;     float v[4];
; #pragma unroll
;     for (int j = 0; j < 4; ++j) { const float a = xa[j]; v[j] = a * sigmoidf_(a) * xb[j]; }
;     uint2 o; o.x = pk_bf16(v[0], v[1]); o.y = pk_bf16(v[2], v[3]);
;     *(uint2*)(act + (size_t)row * DFF + oc) = o;
	global_store_dwordx2 v195, v[76:77], s[44:45] offset:128
	v_pk_mul_f32 v[176:177], v[64:65], v[198:199]
	v_pk_mul_f32 v[178:179], v[66:67], v[198:199]
	v_pk_mul_f32 v[184:185], v[56:57], v[198:199]
	v_pk_mul_f32 v[186:187], v[58:59], v[198:199]
	v_exp_f32_e32 v176, v176
	v_exp_f32_e32 v177, v177
	v_exp_f32_e32 v178, v178
	v_exp_f32_e32 v179, v179
	v_exp_f32_e32 v184, v184
	v_exp_f32_e32 v185, v185
	v_exp_f32_e32 v186, v186
	v_exp_f32_e32 v187, v187
	v_pk_add_f32 v[176:177], v[196:197], v[176:177]
	v_pk_add_f32 v[178:179], v[196:197], v[178:179]
	v_pk_add_f32 v[184:185], v[196:197], v[184:185]
	v_pk_add_f32 v[186:187], v[196:197], v[186:187]
	v_rcp_f32_e32 v176, v176
	v_rcp_f32_e32 v177, v177
	v_rcp_f32_e32 v178, v178
	v_rcp_f32_e32 v179, v179
	v_rcp_f32_e32 v184, v184
	v_rcp_f32_e32 v185, v185
	v_rcp_f32_e32 v186, v186
	v_rcp_f32_e32 v187, v187
	v_pk_mul_f32 v[64:65], v[64:65], v[176:177]
	v_pk_mul_f32 v[66:67], v[66:67], v[178:179]
	v_pk_mul_f32 v[56:57], v[56:57], v[184:185]
	v_pk_mul_f32 v[58:59], v[58:59], v[186:187]
	v_pk_mul_f32 v[64:65], v[68:69], v[64:65]
	v_pk_mul_f32 v[66:67], v[70:71], v[66:67]
	v_pk_mul_f32 v[56:57], v[60:61], v[56:57]
	v_pk_mul_f32 v[58:59], v[62:63], v[58:59]
	v_cvt_pk_bf16_f32 v68, v64, v65
	v_cvt_pk_bf16_f32 v69, v66, v67
	v_cvt_pk_bf16_f32 v60, v56, v57
	v_cvt_pk_bf16_f32 v61, v58, v59
	global_store_dwordx2 v192, v[68:69], s[46:47]
	global_store_dwordx2 v193, v[60:61], s[46:47]
	v_pk_mul_f32 v[176:177], v[48:49], v[198:199]
	v_pk_mul_f32 v[178:179], v[50:51], v[198:199]
	v_pk_mul_f32 v[184:185], v[40:41], v[198:199]
	v_pk_mul_f32 v[186:187], v[42:43], v[198:199]
	v_exp_f32_e32 v176, v176
	v_exp_f32_e32 v177, v177
	v_exp_f32_e32 v178, v178
	v_exp_f32_e32 v179, v179
	v_exp_f32_e32 v184, v184
	v_exp_f32_e32 v185, v185
	v_exp_f32_e32 v186, v186
	v_exp_f32_e32 v187, v187
	v_pk_add_f32 v[176:177], v[196:197], v[176:177]
	v_pk_add_f32 v[178:179], v[196:197], v[178:179]
	v_pk_add_f32 v[184:185], v[196:197], v[184:185]
	v_pk_add_f32 v[186:187], v[196:197], v[186:187]
	v_rcp_f32_e32 v176, v176
	v_rcp_f32_e32 v177, v177
	v_rcp_f32_e32 v178, v178
	v_rcp_f32_e32 v179, v179
	v_rcp_f32_e32 v184, v184
	v_rcp_f32_e32 v185, v185
	v_rcp_f32_e32 v186, v186
	v_rcp_f32_e32 v187, v187
	v_pk_mul_f32 v[48:49], v[48:49], v[176:177]
	v_pk_mul_f32 v[50:51], v[50:51], v[178:179]
	v_pk_mul_f32 v[40:41], v[40:41], v[184:185]
	v_pk_mul_f32 v[42:43], v[42:43], v[186:187]
	v_pk_mul_f32 v[48:49], v[52:53], v[48:49]
	v_pk_mul_f32 v[50:51], v[54:55], v[50:51]
	v_pk_mul_f32 v[40:41], v[44:45], v[40:41]
	v_pk_mul_f32 v[42:43], v[46:47], v[42:43]
	v_cvt_pk_bf16_f32 v52, v48, v49
	v_cvt_pk_bf16_f32 v53, v50, v51
	v_cvt_pk_bf16_f32 v44, v40, v41
	v_cvt_pk_bf16_f32 v45, v42, v43
	global_store_dwordx2 v194, v[52:53], s[46:47]
	global_store_dwordx2 v195, v[44:45], s[46:47]
	v_pk_mul_f32 v[176:177], v[32:33], v[198:199]
	v_pk_mul_f32 v[178:179], v[34:35], v[198:199]
	v_pk_mul_f32 v[184:185], v[24:25], v[198:199]
	v_pk_mul_f32 v[186:187], v[26:27], v[198:199]
	v_exp_f32_e32 v176, v176
	v_exp_f32_e32 v177, v177
	v_exp_f32_e32 v178, v178
	v_exp_f32_e32 v179, v179
	v_exp_f32_e32 v184, v184
	v_exp_f32_e32 v185, v185
	v_exp_f32_e32 v186, v186
	v_exp_f32_e32 v187, v187
	v_pk_add_f32 v[176:177], v[196:197], v[176:177]
	v_pk_add_f32 v[178:179], v[196:197], v[178:179]
	v_pk_add_f32 v[184:185], v[196:197], v[184:185]
	v_pk_add_f32 v[186:187], v[196:197], v[186:187]
	v_rcp_f32_e32 v176, v176
	v_rcp_f32_e32 v177, v177
	v_rcp_f32_e32 v178, v178
	v_rcp_f32_e32 v179, v179
	v_rcp_f32_e32 v184, v184
	v_rcp_f32_e32 v185, v185
	v_rcp_f32_e32 v186, v186
	v_rcp_f32_e32 v187, v187
	v_pk_mul_f32 v[32:33], v[32:33], v[176:177]
	v_pk_mul_f32 v[34:35], v[34:35], v[178:179]
	v_pk_mul_f32 v[24:25], v[24:25], v[184:185]
	v_pk_mul_f32 v[26:27], v[26:27], v[186:187]
	v_pk_mul_f32 v[32:33], v[36:37], v[32:33]
	v_pk_mul_f32 v[34:35], v[38:39], v[34:35]
	v_pk_mul_f32 v[24:25], v[28:29], v[24:25]
	v_pk_mul_f32 v[26:27], v[30:31], v[26:27]
	v_cvt_pk_bf16_f32 v36, v32, v33
	v_cvt_pk_bf16_f32 v37, v34, v35
	v_cvt_pk_bf16_f32 v28, v24, v25
	v_cvt_pk_bf16_f32 v29, v26, v27
	global_store_dwordx2 v192, v[36:37], s[46:47] offset:128
	global_store_dwordx2 v193, v[28:29], s[46:47] offset:128
	v_pk_mul_f32 v[176:177], v[16:17], v[198:199]
	v_pk_mul_f32 v[178:179], v[18:19], v[198:199]
	v_pk_mul_f32 v[184:185], v[8:9], v[198:199]
	v_pk_mul_f32 v[186:187], v[10:11], v[198:199]
	v_exp_f32_e32 v176, v176
	v_exp_f32_e32 v177, v177
	v_exp_f32_e32 v178, v178
	v_exp_f32_e32 v179, v179
	v_exp_f32_e32 v184, v184
	v_exp_f32_e32 v185, v185
	v_exp_f32_e32 v186, v186
	v_exp_f32_e32 v187, v187
	v_pk_add_f32 v[176:177], v[196:197], v[176:177]
	v_pk_add_f32 v[178:179], v[196:197], v[178:179]
	v_pk_add_f32 v[184:185], v[196:197], v[184:185]
	v_pk_add_f32 v[186:187], v[196:197], v[186:187]
	v_rcp_f32_e32 v176, v176
	v_rcp_f32_e32 v177, v177
	v_rcp_f32_e32 v178, v178
	v_rcp_f32_e32 v179, v179
	v_rcp_f32_e32 v184, v184
	v_rcp_f32_e32 v185, v185
	v_rcp_f32_e32 v186, v186
	v_rcp_f32_e32 v187, v187
	v_pk_mul_f32 v[16:17], v[16:17], v[176:177]
	v_pk_mul_f32 v[18:19], v[18:19], v[178:179]
	v_pk_mul_f32 v[8:9], v[8:9], v[184:185]
	v_pk_mul_f32 v[10:11], v[10:11], v[186:187]
	v_pk_mul_f32 v[16:17], v[20:21], v[16:17]
	v_pk_mul_f32 v[18:19], v[22:23], v[18:19]
	v_pk_mul_f32 v[8:9], v[12:13], v[8:9]
	v_pk_mul_f32 v[10:11], v[14:15], v[10:11]
	v_cvt_pk_bf16_f32 v20, v16, v17
	v_cvt_pk_bf16_f32 v21, v18, v19
	v_cvt_pk_bf16_f32 v12, v8, v9
	v_cvt_pk_bf16_f32 v13, v10, v11
	global_store_dwordx2 v194, v[20:21], s[46:47] offset:128
	global_store_dwordx2 v195, v[12:13], s[46:47] offset:128
	s_mov_b32 s18, s37
	s_mov_b32 s17, s36
	s_mov_b32 s16, s40
	s_andn2_b64 vcc, exec, s[8:9]
	s_cbranch_vccz .LBB0_739
	s_branch .LBB0_675
